# v99 + GEMM main-loop MFMAs reordered inside each group of 8 (A-fragment-major snake order: fewer operand changes between consecutive MFMAs)
# baseline (speedup 1.0000x reference)
; #define PG8_STAGE(bufoff, gbase, voff) do { _Pragma("unroll") for (int _i = 0; _i < 2; ++_i) \
;         __builtin_amdgcn_global_load_lds((const unsigned*)((const char*)(gbase) + (voff)[_i]), (LAS unsigned*)(lds + (bufoff) + ldsw + _i * 8192), 16, 0, 0); } while (0)
; #define PG8_LDA(dst, b, h) do { _Pragma("unroll") for (int m = 0; m < 4; ++m) _Pragma("unroll") for (int k = 0; k < 2; ++k) dst[m][k] = *(const LAS bf16x8*)(lds + PG8_SA(b, h) + aoff + m * 2048 + k * 1024); } while (0)
; #define PG8_LDB(dst, b, h) do { _Pragma("unroll") for (int n = 0; n < 2; ++n) _Pragma("unroll") for (int k = 0; k < 2; ++k) dst[n][k] = *(const LAS bf16x8*)(lds + PG8_SB(b, h) + boff + n * 2048 + k * 1024); } while (0)
; #define PG8_MMA(ai, bj, At, Bt) do { __builtin_amdgcn_s_setprio(1); _Pragma("unroll") for (int m = 0; m < 4; ++m) _Pragma("unroll") for (int n = 0; n < 2; ++n) _Pragma("unroll") for (int k = 0; k < 2; ++k) \
;         acc[ai][bj][m][n] = __builtin_amdgcn_mfma_f32_16x16x32_bf16(Bt[n][k], At[m][k], acc[ai][bj][m][n], 0, 0, 0); __builtin_amdgcn_s_setprio(0); } while (0)
; #define PG8_WAIT_V(n) asm volatile("s_waitcnt vmcnt(" #n ")" ::: "memory")
; #define PG8_WAIT_L(n) asm volatile("s_waitcnt lgkmcnt(" #n ")" ::: "memory")
; #define PG8_BAR __builtin_amdgcn_s_barrier()
; #define PG8_SCHED __builtin_amdgcn_sched_barrier(0)
; template <class Epi, class Sched>
; __device__ __forceinline__ void gemm_phase(LAS unsigned char* lds, const Gemm g, const Sched& S, const Epi& E, const int tid) {
;     ...
;             PG8_LDB(B0, 0, 0); PG8_LDB(B1, 0, 1); PG8_SCHED; PG8_LDA(At, 0, 0); PG8_STAGE(PG8_SA(1, 1), a1 + hstep, voffA);
;             PG8_WAIT_V(8); PG8_WAIT_L(0); PG8_BAR; PG8_MMA(0, 0, At, B0); PG8_MMA(0, 1, At, B1); PG8_BAR; PG8_SCHED;
;             PG8_LDA(At, 0, 1); PG8_STAGE(PG8_SB(0, 0), b2, voffB); PG8_STAGE(PG8_SB(0, 1), b2 + hstep, voffB); PG8_STAGE(PG8_SA(0, 0), a2, voffA);
;             PG8_WAIT_V(8); PG8_WAIT_L(0); PG8_BAR; PG8_MMA(1, 0, At, B0); PG8_MMA(1, 1, At, B1); PG8_BAR; PG8_SCHED;
.LBB0_385:
	s_add_i32 s85, s31, 2
	s_add_u32 s30, s66, 0x80
	s_addc_u32 s68, s67, 0
	s_add_i32 s86, 0, 0x10000
	s_cmp_eq_u32 s38, s31
	s_cselect_b32 s69, s5, s68
	s_cselect_b32 s68, s4, s30
	v_add_u32_e32 v152, s86, v141
	s_cselect_b32 s31, s65, s84
	s_cselect_b32 s30, s64, s71
	s_add_i32 s87, 0, 0x14000
	ds_read_b128 v[144:147], v152
	ds_read_b128 v[148:151], v152 offset:1024
	ds_read_b128 v[174:177], v152 offset:2048
	ds_read_b128 v[178:181], v152 offset:3072
	v_add_u32_e32 v152, s87, v141
	ds_read_b128 v[182:185], v152
	ds_read_b128 v[186:189], v152 offset:1024
	ds_read_b128 v[190:193], v152 offset:2048
	ds_read_b128 v[194:197], v152 offset:3072
	v_lshl_add_u64 v[152:153], s[66:67], 0, v[138:139]
	s_add_i32 m0, s23, 0xc000
	ds_read_b128 v[210:213], v143
	ds_read_b128 v[214:217], v143 offset:1024
	ds_read_b128 v[218:221], v143 offset:2048
	ds_read_b128 v[222:225], v143 offset:3072
	ds_read_b128 v[226:229], v143 offset:4096
	ds_read_b128 v[230:233], v143 offset:5120
	ds_read_b128 v[234:237], v143 offset:6144
	ds_read_b128 v[238:241], v143 offset:7168
	global_load_lds_dwordx4 v[152:153], off
	v_lshl_add_u64 v[152:153], s[66:67], 0, v[136:137]
	s_add_i32 m0, s23, 0xe000
	s_nop 0
	global_load_lds_dwordx4 v[152:153], off
	s_waitcnt vmcnt(8)
	s_waitcnt lgkmcnt(0)
	s_barrier
	s_setprio 1
	s_waitcnt lgkmcnt(0)
	v_mfma_f32_16x16x32_bf16 v[126:129], v[144:147], v[210:213], v[126:129]
	v_mfma_f32_16x16x32_bf16 v[110:113], v[144:147], v[218:221], v[110:113]
	v_mfma_f32_16x16x32_bf16 v[94:97], v[144:147], v[226:229], v[94:97]
	v_mfma_f32_16x16x32_bf16 v[78:81], v[144:147], v[234:237], v[78:81]
	v_mfma_f32_16x16x32_bf16 v[74:77], v[174:177], v[234:237], v[74:77]
	v_mfma_f32_16x16x32_bf16 v[90:93], v[174:177], v[226:229], v[90:93]
	v_mfma_f32_16x16x32_bf16 v[106:109], v[174:177], v[218:221], v[106:109]
	v_mfma_f32_16x16x32_bf16 v[122:125], v[174:177], v[210:213], v[122:125]
	v_mfma_f32_16x16x32_bf16 v[126:129], v[148:151], v[214:217], v[126:129]
	v_mfma_f32_16x16x32_bf16 v[110:113], v[148:151], v[222:225], v[110:113]
	v_mfma_f32_16x16x32_bf16 v[94:97], v[148:151], v[230:233], v[94:97]
	v_mfma_f32_16x16x32_bf16 v[78:81], v[148:151], v[238:241], v[78:81]
	v_mfma_f32_16x16x32_bf16 v[74:77], v[178:181], v[238:241], v[74:77]
	v_mfma_f32_16x16x32_bf16 v[90:93], v[178:181], v[230:233], v[90:93]
	v_mfma_f32_16x16x32_bf16 v[106:109], v[178:181], v[222:225], v[106:109]
	v_mfma_f32_16x16x32_bf16 v[122:125], v[178:181], v[214:217], v[122:125]
	s_setprio 0
	s_setprio 1
	v_mfma_f32_16x16x32_bf16 v[118:121], v[182:185], v[210:213], v[118:121]
	v_mfma_f32_16x16x32_bf16 v[102:105], v[182:185], v[218:221], v[102:105]
	v_mfma_f32_16x16x32_bf16 v[86:89], v[182:185], v[226:229], v[86:89]
	v_mfma_f32_16x16x32_bf16 v[70:73], v[182:185], v[234:237], v[70:73]
	v_mfma_f32_16x16x32_bf16 v[66:69], v[190:193], v[234:237], v[66:69]
	v_mfma_f32_16x16x32_bf16 v[82:85], v[190:193], v[226:229], v[82:85]
	v_mfma_f32_16x16x32_bf16 v[98:101], v[190:193], v[218:221], v[98:101]
	v_mfma_f32_16x16x32_bf16 v[114:117], v[190:193], v[210:213], v[114:117]
	v_mfma_f32_16x16x32_bf16 v[118:121], v[186:189], v[214:217], v[118:121]
	v_mfma_f32_16x16x32_bf16 v[102:105], v[186:189], v[222:225], v[102:105]
	v_mfma_f32_16x16x32_bf16 v[86:89], v[186:189], v[230:233], v[86:89]
	v_mfma_f32_16x16x32_bf16 v[70:73], v[186:189], v[238:241], v[70:73]
	v_mfma_f32_16x16x32_bf16 v[66:69], v[194:197], v[238:241], v[66:69]
	v_mfma_f32_16x16x32_bf16 v[82:85], v[194:197], v[230:233], v[82:85]
	v_mfma_f32_16x16x32_bf16 v[98:101], v[194:197], v[222:225], v[98:101]
	v_mfma_f32_16x16x32_bf16 v[114:117], v[194:197], v[214:217], v[114:117]
	s_setprio 0
	s_barrier
	s_add_i32 s86, s86, s20
	v_lshl_add_u64 v[152:153], s[30:31], 0, v[0:1]
	s_mov_b32 m0, s86
	ds_read_b128 v[210:213], v143 offset:16384
	ds_read_b128 v[214:217], v143 offset:17408
	ds_read_b128 v[218:221], v143 offset:18432
	ds_read_b128 v[222:225], v143 offset:19456
	ds_read_b128 v[226:229], v143 offset:20480
	ds_read_b128 v[230:233], v143 offset:21504
	ds_read_b128 v[234:237], v143 offset:22528
	ds_read_b128 v[238:241], v143 offset:23552
	global_load_lds_dwordx4 v[152:153], off
	s_add_i32 m0, s86, 0x2000
	v_lshl_add_u64 v[168:169], s[30:31], 0, v[134:135]
	s_add_u32 s30, s30, s2
	s_addc_u32 s31, s31, 0
	s_add_i32 s86, s87, s20
	global_load_lds_dwordx4 v[168:169], off
	v_lshl_add_u64 v[198:199], s[30:31], 0, v[0:1]
	s_mov_b32 m0, s86
	v_lshl_add_u64 v[200:201], s[30:31], 0, v[134:135]
	global_load_lds_dwordx4 v[198:199], off
	s_add_i32 m0, s86, 0x2000
	v_lshl_add_u64 v[242:243], s[68:69], 0, v[130:131]
	global_load_lds_dwordx4 v[200:201], off
	s_mov_b32 m0, s23
	v_lshl_add_u64 v[244:245], s[68:69], 0, v[132:133]
	global_load_lds_dwordx4 v[242:243], off
	s_mov_b32 m0, s24
	s_nop 0
	global_load_lds_dwordx4 v[244:245], off
	s_waitcnt vmcnt(8)
	s_waitcnt lgkmcnt(0)
	s_barrier
; #define PG8_STAGE(bufoff, gbase, voff) do { _Pragma("unroll") for (int _i = 0; _i < 2; ++_i) \
;         __builtin_amdgcn_global_load_lds((const unsigned*)((const char*)(gbase) + (voff)[_i]), (LAS unsigned*)(lds + (bufoff) + ldsw + _i * 8192), 16, 0, 0); } while (0)
; #define PG8_LDA(dst, b, h) do { _Pragma("unroll") for (int m = 0; m < 4; ++m) _Pragma("unroll") for (int k = 0; k < 2; ++k) dst[m][k] = *(const LAS bf16x8*)(lds + PG8_SA(b, h) + aoff + m * 2048 + k * 1024); } while (0)
; #define PG8_LDB(dst, b, h) do { _Pragma("unroll") for (int n = 0; n < 2; ++n) _Pragma("unroll") for (int k = 0; k < 2; ++k) dst[n][k] = *(const LAS bf16x8*)(lds + PG8_SB(b, h) + boff + n * 2048 + k * 1024); } while (0)
; #define PG8_MMA(ai, bj, At, Bt) do { __builtin_amdgcn_s_setprio(1); _Pragma("unroll") for (int m = 0; m < 4; ++m) _Pragma("unroll") for (int n = 0; n < 2; ++n) _Pragma("unroll") for (int k = 0; k < 2; ++k) \
;         acc[ai][bj][m][n] = __builtin_amdgcn_mfma_f32_16x16x32_bf16(Bt[n][k], At[m][k], acc[ai][bj][m][n], 0, 0, 0); __builtin_amdgcn_s_setprio(0); } while (0)
; #define PG8_WAIT_V(n) asm volatile("s_waitcnt vmcnt(" #n ")" ::: "memory")
; #define PG8_WAIT_L(n) asm volatile("s_waitcnt lgkmcnt(" #n ")" ::: "memory")
; #define PG8_BAR __builtin_amdgcn_s_barrier()
; #define PG8_SCHED __builtin_amdgcn_sched_barrier(0)
; template <class Epi, class Sched>
; __device__ __forceinline__ void gemm_phase(LAS unsigned char* lds, const Gemm g, const Sched& S, const Epi& E, const int tid) {
;     ...
;             PG8_WAIT_V(8); PG8_WAIT_L(0); PG8_BAR; PG8_MMA(1, 0, At, B0); PG8_MMA(1, 1, At, B1); PG8_BAR; PG8_SCHED;
;             PG8_LDB(B0, 1, 0); PG8_LDB(B1, 1, 1); PG8_SCHED; PG8_LDA(At, 1, 0); PG8_STAGE(PG8_SA(0, 1), a2 + hstep, voffA);
;             PG8_WAIT_V(8); PG8_WAIT_L(0); PG8_BAR; PG8_MMA(0, 0, At, B0); PG8_MMA(0, 1, At, B1); PG8_BAR; PG8_SCHED;
	s_setprio 1
	s_waitcnt lgkmcnt(0)
	v_mfma_f32_16x16x32_bf16 v[62:65], v[144:147], v[210:213], v[62:65]
	v_mfma_f32_16x16x32_bf16 v[46:49], v[144:147], v[218:221], v[46:49]
	v_mfma_f32_16x16x32_bf16 v[30:33], v[144:147], v[226:229], v[30:33]
	v_mfma_f32_16x16x32_bf16 v[14:17], v[144:147], v[234:237], v[14:17]
	v_mfma_f32_16x16x32_bf16 v[10:13], v[174:177], v[234:237], v[10:13]
	v_mfma_f32_16x16x32_bf16 v[26:29], v[174:177], v[226:229], v[26:29]
	v_mfma_f32_16x16x32_bf16 v[42:45], v[174:177], v[218:221], v[42:45]
	v_mfma_f32_16x16x32_bf16 v[58:61], v[174:177], v[210:213], v[58:61]
	v_mfma_f32_16x16x32_bf16 v[62:65], v[148:151], v[214:217], v[62:65]
	v_mfma_f32_16x16x32_bf16 v[46:49], v[148:151], v[222:225], v[46:49]
	v_mfma_f32_16x16x32_bf16 v[30:33], v[148:151], v[230:233], v[30:33]
	v_mfma_f32_16x16x32_bf16 v[14:17], v[148:151], v[238:241], v[14:17]
	v_mfma_f32_16x16x32_bf16 v[10:13], v[178:181], v[238:241], v[10:13]
	v_mfma_f32_16x16x32_bf16 v[26:29], v[178:181], v[230:233], v[26:29]
	v_mfma_f32_16x16x32_bf16 v[42:45], v[178:181], v[222:225], v[42:45]
	v_mfma_f32_16x16x32_bf16 v[58:61], v[178:181], v[214:217], v[58:61]
	s_setprio 0
	s_setprio 1
	v_mfma_f32_16x16x32_bf16 v[54:57], v[182:185], v[210:213], v[54:57]
	v_mfma_f32_16x16x32_bf16 v[38:41], v[182:185], v[218:221], v[38:41]
	v_mfma_f32_16x16x32_bf16 v[22:25], v[182:185], v[226:229], v[22:25]
	v_mfma_f32_16x16x32_bf16 v[6:9], v[182:185], v[234:237], v[6:9]
	v_mfma_f32_16x16x32_bf16 v[2:5], v[190:193], v[234:237], v[2:5]
	v_mfma_f32_16x16x32_bf16 v[18:21], v[190:193], v[226:229], v[18:21]
	v_mfma_f32_16x16x32_bf16 v[34:37], v[190:193], v[218:221], v[34:37]
	v_mfma_f32_16x16x32_bf16 v[50:53], v[190:193], v[210:213], v[50:53]
	v_mfma_f32_16x16x32_bf16 v[54:57], v[186:189], v[214:217], v[54:57]
	v_mfma_f32_16x16x32_bf16 v[38:41], v[186:189], v[222:225], v[38:41]
	v_mfma_f32_16x16x32_bf16 v[22:25], v[186:189], v[230:233], v[22:25]
	v_mfma_f32_16x16x32_bf16 v[6:9], v[186:189], v[238:241], v[6:9]
	v_mfma_f32_16x16x32_bf16 v[2:5], v[194:197], v[238:241], v[2:5]
	v_mfma_f32_16x16x32_bf16 v[18:21], v[194:197], v[230:233], v[18:21]
	v_mfma_f32_16x16x32_bf16 v[34:37], v[194:197], v[222:225], v[34:37]
	v_mfma_f32_16x16x32_bf16 v[50:53], v[194:197], v[214:217], v[50:53]
	s_setprio 0
	s_barrier
	s_add_i32 s86, 0, 0x18000
	v_add_u32_e32 v173, s86, v141
	s_add_i32 s87, 0, 0x1c000
	ds_read_b128 v[144:147], v173
	ds_read_b128 v[148:151], v173 offset:1024
	ds_read_b128 v[174:177], v173 offset:2048
	ds_read_b128 v[178:181], v173 offset:3072
	v_add_u32_e32 v173, s87, v141
	ds_read_b128 v[182:185], v173
	ds_read_b128 v[186:189], v173 offset:1024
	ds_read_b128 v[190:193], v173 offset:2048
	ds_read_b128 v[194:197], v173 offset:3072
	s_add_u32 s30, s68, s2
	s_addc_u32 s31, s69, 0
	s_mov_b32 m0, s25
	v_lshl_add_u64 v[246:247], s[30:31], 0, v[130:131]
	ds_read_b128 v[210:213], v143 offset:32768
	ds_read_b128 v[214:217], v143 offset:33792
	ds_read_b128 v[218:221], v143 offset:34816
	ds_read_b128 v[222:225], v143 offset:35840
	ds_read_b128 v[226:229], v143 offset:36864
	ds_read_b128 v[230:233], v143 offset:37888
	ds_read_b128 v[234:237], v143 offset:38912
	ds_read_b128 v[238:241], v143 offset:39936
	global_load_lds_dwordx4 v[246:247], off
	v_lshl_add_u64 v[246:247], s[30:31], 0, v[132:133]
	s_mov_b32 m0, s26
	s_nop 0
	global_load_lds_dwordx4 v[246:247], off
	s_waitcnt vmcnt(8)
	s_waitcnt lgkmcnt(0)
	s_barrier
	s_setprio 1
	s_waitcnt lgkmcnt(0)
	v_mfma_f32_16x16x32_bf16 v[126:129], v[144:147], v[210:213], v[126:129]
	v_mfma_f32_16x16x32_bf16 v[110:113], v[144:147], v[218:221], v[110:113]
	v_mfma_f32_16x16x32_bf16 v[94:97], v[144:147], v[226:229], v[94:97]
	v_mfma_f32_16x16x32_bf16 v[78:81], v[144:147], v[234:237], v[78:81]
	v_mfma_f32_16x16x32_bf16 v[74:77], v[174:177], v[234:237], v[74:77]
	v_mfma_f32_16x16x32_bf16 v[90:93], v[174:177], v[226:229], v[90:93]
	v_mfma_f32_16x16x32_bf16 v[106:109], v[174:177], v[218:221], v[106:109]
	v_mfma_f32_16x16x32_bf16 v[122:125], v[174:177], v[210:213], v[122:125]
	v_mfma_f32_16x16x32_bf16 v[126:129], v[148:151], v[214:217], v[126:129]
	v_mfma_f32_16x16x32_bf16 v[110:113], v[148:151], v[222:225], v[110:113]
	v_mfma_f32_16x16x32_bf16 v[94:97], v[148:151], v[230:233], v[94:97]
	v_mfma_f32_16x16x32_bf16 v[78:81], v[148:151], v[238:241], v[78:81]
	v_mfma_f32_16x16x32_bf16 v[74:77], v[178:181], v[238:241], v[74:77]
	v_mfma_f32_16x16x32_bf16 v[90:93], v[178:181], v[230:233], v[90:93]
	v_mfma_f32_16x16x32_bf16 v[106:109], v[178:181], v[222:225], v[106:109]
	v_mfma_f32_16x16x32_bf16 v[122:125], v[178:181], v[214:217], v[122:125]
	s_setprio 0
	s_setprio 1
	v_mfma_f32_16x16x32_bf16 v[118:121], v[182:185], v[210:213], v[118:121]
	v_mfma_f32_16x16x32_bf16 v[102:105], v[182:185], v[218:221], v[102:105]
	v_mfma_f32_16x16x32_bf16 v[86:89], v[182:185], v[226:229], v[86:89]
	v_mfma_f32_16x16x32_bf16 v[70:73], v[182:185], v[234:237], v[70:73]
	v_mfma_f32_16x16x32_bf16 v[66:69], v[190:193], v[234:237], v[66:69]
	v_mfma_f32_16x16x32_bf16 v[82:85], v[190:193], v[226:229], v[82:85]
	v_mfma_f32_16x16x32_bf16 v[98:101], v[190:193], v[218:221], v[98:101]
	v_mfma_f32_16x16x32_bf16 v[114:117], v[190:193], v[210:213], v[114:117]
	v_mfma_f32_16x16x32_bf16 v[118:121], v[186:189], v[214:217], v[118:121]
	v_mfma_f32_16x16x32_bf16 v[102:105], v[186:189], v[222:225], v[102:105]
	v_mfma_f32_16x16x32_bf16 v[86:89], v[186:189], v[230:233], v[86:89]
	v_mfma_f32_16x16x32_bf16 v[70:73], v[186:189], v[238:241], v[70:73]
	v_mfma_f32_16x16x32_bf16 v[66:69], v[194:197], v[238:241], v[66:69]
	v_mfma_f32_16x16x32_bf16 v[82:85], v[194:197], v[230:233], v[82:85]
	v_mfma_f32_16x16x32_bf16 v[98:101], v[194:197], v[222:225], v[98:101]
	v_mfma_f32_16x16x32_bf16 v[114:117], v[194:197], v[214:217], v[114:117]
	s_setprio 0
	s_barrier
; #define PG8_STAGE(bufoff, gbase, voff) do { _Pragma("unroll") for (int _i = 0; _i < 2; ++_i) \
;         __builtin_amdgcn_global_load_lds((const unsigned*)((const char*)(gbase) + (voff)[_i]), (LAS unsigned*)(lds + (bufoff) + ldsw + _i * 8192), 16, 0, 0); } while (0)
; #define PG8_LDA(dst, b, h) do { _Pragma("unroll") for (int m = 0; m < 4; ++m) _Pragma("unroll") for (int k = 0; k < 2; ++k) dst[m][k] = *(const LAS bf16x8*)(lds + PG8_SA(b, h) + aoff + m * 2048 + k * 1024); } while (0)
; #define PG8_MMA(ai, bj, At, Bt) do { __builtin_amdgcn_s_setprio(1); _Pragma("unroll") for (int m = 0; m < 4; ++m) _Pragma("unroll") for (int n = 0; n < 2; ++n) _Pragma("unroll") for (int k = 0; k < 2; ++k) \
;         acc[ai][bj][m][n] = __builtin_amdgcn_mfma_f32_16x16x32_bf16(Bt[n][k], At[m][k], acc[ai][bj][m][n], 0, 0, 0); __builtin_amdgcn_s_setprio(0); } while (0)
; #define PG8_WAIT_V(n) asm volatile("s_waitcnt vmcnt(" #n ")" ::: "memory")
; #define PG8_WAIT_L(n) asm volatile("s_waitcnt lgkmcnt(" #n ")" ::: "memory")
; #define PG8_BAR __builtin_amdgcn_s_barrier()
; #define PG8_SCHED __builtin_amdgcn_sched_barrier(0)
; template <class Epi, class Sched>
; __device__ __forceinline__ void gemm_phase(LAS unsigned char* lds, const Gemm g, const Sched& S, const Epi& E, const int tid) {
;     ...
;             PG8_LDA(At, 1, 1); PG8_STAGE(PG8_SB(1, 0), b3, voffB); PG8_STAGE(PG8_SB(1, 1), b3 + hstep, voffB); PG8_STAGE(PG8_SA(1, 0), a3, voffA);
;             PG8_WAIT_V(8); PG8_WAIT_L(0); PG8_BAR; PG8_MMA(1, 0, At, B0); PG8_MMA(1, 1, At, B1); PG8_BAR; PG8_SCHED;
;         }
	s_add_i32 s30, s86, s20
	v_lshl_add_u64 v[152:153], v[152:153], 0, s[74:75]
	s_mov_b32 m0, s30
	ds_read_b128 v[210:213], v143 offset:49152
	ds_read_b128 v[214:217], v143 offset:50176
	ds_read_b128 v[218:221], v143 offset:51200
	ds_read_b128 v[222:225], v143 offset:52224
	ds_read_b128 v[226:229], v143 offset:53248
	ds_read_b128 v[230:233], v143 offset:54272
	ds_read_b128 v[234:237], v143 offset:55296
	ds_read_b128 v[238:241], v143 offset:56320
	global_load_lds_dwordx4 v[152:153], off
	v_lshl_add_u64 v[152:153], v[168:169], 0, s[74:75]
	s_add_i32 m0, s30, 0x2000
	s_add_i32 s30, s87, s20
	global_load_lds_dwordx4 v[152:153], off
	v_lshl_add_u64 v[152:153], v[198:199], 0, s[74:75]
	s_mov_b32 m0, s30
	s_nop 0
	global_load_lds_dwordx4 v[152:153], off
	v_lshl_add_u64 v[152:153], v[200:201], 0, s[74:75]
	s_add_i32 m0, s30, 0x2000
	s_nop 0
	global_load_lds_dwordx4 v[152:153], off
	v_lshl_add_u64 v[152:153], v[242:243], 0, s[74:75]
	s_mov_b32 m0, s36
	s_nop 0
	global_load_lds_dwordx4 v[152:153], off
	v_lshl_add_u64 v[152:153], v[244:245], 0, s[74:75]
	s_mov_b32 m0, s37
	s_nop 0
	global_load_lds_dwordx4 v[152:153], off
	s_waitcnt vmcnt(8)
	s_waitcnt lgkmcnt(0)
	s_barrier
	s_setprio 1
	s_waitcnt lgkmcnt(0)
	v_mfma_f32_16x16x32_bf16 v[62:65], v[144:147], v[210:213], v[62:65]
	v_mfma_f32_16x16x32_bf16 v[46:49], v[144:147], v[218:221], v[46:49]
	v_mfma_f32_16x16x32_bf16 v[30:33], v[144:147], v[226:229], v[30:33]
	v_mfma_f32_16x16x32_bf16 v[14:17], v[144:147], v[234:237], v[14:17]
	v_mfma_f32_16x16x32_bf16 v[10:13], v[174:177], v[234:237], v[10:13]
	v_mfma_f32_16x16x32_bf16 v[26:29], v[174:177], v[226:229], v[26:29]
	v_mfma_f32_16x16x32_bf16 v[42:45], v[174:177], v[218:221], v[42:45]
	v_mfma_f32_16x16x32_bf16 v[58:61], v[174:177], v[210:213], v[58:61]
	v_mfma_f32_16x16x32_bf16 v[62:65], v[148:151], v[214:217], v[62:65]
	v_mfma_f32_16x16x32_bf16 v[46:49], v[148:151], v[222:225], v[46:49]
	v_mfma_f32_16x16x32_bf16 v[30:33], v[148:151], v[230:233], v[30:33]
	v_mfma_f32_16x16x32_bf16 v[14:17], v[148:151], v[238:241], v[14:17]
	v_mfma_f32_16x16x32_bf16 v[10:13], v[178:181], v[238:241], v[10:13]
	v_mfma_f32_16x16x32_bf16 v[26:29], v[178:181], v[230:233], v[26:29]
	v_mfma_f32_16x16x32_bf16 v[42:45], v[178:181], v[222:225], v[42:45]
	v_mfma_f32_16x16x32_bf16 v[58:61], v[178:181], v[214:217], v[58:61]
	s_setprio 0
	s_setprio 1
	v_mfma_f32_16x16x32_bf16 v[54:57], v[182:185], v[210:213], v[54:57]
	v_mfma_f32_16x16x32_bf16 v[38:41], v[182:185], v[218:221], v[38:41]
	v_mfma_f32_16x16x32_bf16 v[22:25], v[182:185], v[226:229], v[22:25]
	v_mfma_f32_16x16x32_bf16 v[6:9], v[182:185], v[234:237], v[6:9]
	v_mfma_f32_16x16x32_bf16 v[2:5], v[190:193], v[234:237], v[2:5]
	v_mfma_f32_16x16x32_bf16 v[18:21], v[190:193], v[226:229], v[18:21]
	v_mfma_f32_16x16x32_bf16 v[34:37], v[190:193], v[218:221], v[34:37]
	v_mfma_f32_16x16x32_bf16 v[50:53], v[190:193], v[210:213], v[50:53]
	v_mfma_f32_16x16x32_bf16 v[54:57], v[186:189], v[214:217], v[54:57]
	v_mfma_f32_16x16x32_bf16 v[38:41], v[186:189], v[222:225], v[38:41]
	v_mfma_f32_16x16x32_bf16 v[22:25], v[186:189], v[230:233], v[22:25]
	v_mfma_f32_16x16x32_bf16 v[6:9], v[186:189], v[238:241], v[6:9]
	v_mfma_f32_16x16x32_bf16 v[2:5], v[194:197], v[238:241], v[2:5]
	v_mfma_f32_16x16x32_bf16 v[18:21], v[194:197], v[230:233], v[18:21]
	v_mfma_f32_16x16x32_bf16 v[34:37], v[194:197], v[222:225], v[34:37]
	v_mfma_f32_16x16x32_bf16 v[50:53], v[194:197], v[214:217], v[50:53]
	s_setprio 0
	s_barrier
	s_add_u32 s71, s71, 0x100
	s_addc_u32 s84, s84, 0
	s_add_u32 s66, s66, 0x100
	s_addc_u32 s67, s67, 0
	s_cmp_ge_u32 s85, s27
	s_mov_b32 s31, s85
	s_cbranch_scc0 .LBB0_385
	s_and_b64 vcc, exec, s[62:63]
	s_cbranch_vccz .LBB0_388
	s_barrier

; #define PG8_STAGE(bufoff, gbase, voff) do { _Pragma("unroll") for (int _i = 0; _i < 2; ++_i) \
;         __builtin_amdgcn_global_load_lds((const unsigned*)((const char*)(gbase) + (voff)[_i]), (LAS unsigned*)(lds + (bufoff) + ldsw + _i * 8192), 16, 0, 0); } while (0)
; #define PG8_LDA(dst, b, h) do { _Pragma("unroll") for (int m = 0; m < 4; ++m) _Pragma("unroll") for (int k = 0; k < 2; ++k) dst[m][k] = *(const LAS bf16x8*)(lds + PG8_SA(b, h) + aoff + m * 2048 + k * 1024); } while (0)
; #define PG8_LDB(dst, b, h) do { _Pragma("unroll") for (int n = 0; n < 2; ++n) _Pragma("unroll") for (int k = 0; k < 2; ++k) dst[n][k] = *(const LAS bf16x8*)(lds + PG8_SB(b, h) + boff + n * 2048 + k * 1024); } while (0)
; #define PG8_MMA(ai, bj, At, Bt) do { __builtin_amdgcn_s_setprio(1); _Pragma("unroll") for (int m = 0; m < 4; ++m) _Pragma("unroll") for (int n = 0; n < 2; ++n) _Pragma("unroll") for (int k = 0; k < 2; ++k) \
;         acc[ai][bj][m][n] = __builtin_amdgcn_mfma_f32_16x16x32_bf16(Bt[n][k], At[m][k], acc[ai][bj][m][n], 0, 0, 0); __builtin_amdgcn_s_setprio(0); } while (0)
; #define PG8_WAIT_V(n) asm volatile("s_waitcnt vmcnt(" #n ")" ::: "memory")
; #define PG8_WAIT_L(n) asm volatile("s_waitcnt lgkmcnt(" #n ")" ::: "memory")
; #define PG8_BAR __builtin_amdgcn_s_barrier()
; #define PG8_SCHED __builtin_amdgcn_sched_barrier(0)
; template <class Epi, class Sched>
; __device__ __forceinline__ void gemm_phase(LAS unsigned char* lds, const Gemm g, const Sched& S, const Epi& E, const int tid) {
;     ...
;         for (int t = 0; t < nt; t += 2) {
;             const bool last = (t == nt - 2);
;             const char* a1 = cA + (size_t)(t + 1) * kstep;
;             const char* a2 = last ? nA : cA + (size_t)(t + 2) * kstep; const char* b2 = last ? nB : cB + (size_t)(t + 2) * kstep;
;             const char* a3 = a2 + kstep; const char* b3 = b2 + kstep;
;             PG8_LDB(B0, 0, 0); PG8_LDB(B1, 0, 1); PG8_SCHED; PG8_LDA(At, 0, 0); PG8_STAGE(PG8_SA(1, 1), a1 + hstep, voffA);
;             PG8_WAIT_V(8); PG8_WAIT_L(0); PG8_BAR; PG8_MMA(0, 0, At, B0); PG8_MMA(0, 1, At, B1); PG8_BAR; PG8_SCHED;
;             PG8_LDA(At, 0, 1); PG8_STAGE(PG8_SB(0, 0), b2, voffB); PG8_STAGE(PG8_SB(0, 1), b2 + hstep, voffB); PG8_STAGE(PG8_SA(0, 0), a2, voffA);
.LBB0_417:
	s_add_i32 s96, s31, 2
	s_add_u32 s30, s0, 0x80
	s_addc_u32 s94, s1, 0
	s_add_i32 s97, 0, 0x10000
	s_cmp_eq_u32 s19, s31
	s_cselect_b32 s95, s91, s94
	s_cselect_b32 s94, s90, s30
	v_add_u32_e32 v0, s97, v175
	s_cselect_b32 s31, s93, s99
	s_cselect_b32 s30, s92, s98
	s_add_i32 vcc_lo, 0, 0x14000
	ds_read_b128 v[130:133], v0
	ds_read_b128 v[148:151], v0 offset:1024
	ds_read_b128 v[178:181], v0 offset:2048
	ds_read_b128 v[182:185], v0 offset:3072
	v_add_u32_e32 v0, vcc_lo, v175
	ds_read_b128 v[186:189], v0
	ds_read_b128 v[190:193], v0 offset:1024
	ds_read_b128 v[194:197], v0 offset:2048
	ds_read_b128 v[210:213], v0 offset:3072
	v_lshl_add_u64 v[152:153], s[0:1], 0, v[144:145]
	s_add_i32 m0, s36, 0xc000
	ds_read_b128 v[214:217], v177
	ds_read_b128 v[218:221], v177 offset:1024
	ds_read_b128 v[222:225], v177 offset:2048
	ds_read_b128 v[226:229], v177 offset:3072
	ds_read_b128 v[230:233], v177 offset:4096
	ds_read_b128 v[234:237], v177 offset:5120
	ds_read_b128 v[238:241], v177 offset:6144
	ds_read_b128 v[242:245], v177 offset:7168
	global_load_lds_dwordx4 v[152:153], off
	v_lshl_add_u64 v[152:153], s[0:1], 0, v[142:143]
	s_add_i32 m0, s36, 0xe000
	s_nop 0
	global_load_lds_dwordx4 v[152:153], off
	s_waitcnt vmcnt(8)
	s_waitcnt lgkmcnt(0)
	s_barrier
	s_setprio 1
	s_waitcnt lgkmcnt(0)
	v_mfma_f32_16x16x32_bf16 v[126:129], v[130:133], v[214:217], v[126:129]
	v_mfma_f32_16x16x32_bf16 v[110:113], v[130:133], v[222:225], v[110:113]
	v_mfma_f32_16x16x32_bf16 v[94:97], v[130:133], v[230:233], v[94:97]
	v_mfma_f32_16x16x32_bf16 v[78:81], v[130:133], v[238:241], v[78:81]
	v_mfma_f32_16x16x32_bf16 v[74:77], v[178:181], v[238:241], v[74:77]
	v_mfma_f32_16x16x32_bf16 v[90:93], v[178:181], v[230:233], v[90:93]
	v_mfma_f32_16x16x32_bf16 v[106:109], v[178:181], v[222:225], v[106:109]
	v_mfma_f32_16x16x32_bf16 v[122:125], v[178:181], v[214:217], v[122:125]
	v_mfma_f32_16x16x32_bf16 v[126:129], v[148:151], v[218:221], v[126:129]
	v_mfma_f32_16x16x32_bf16 v[110:113], v[148:151], v[226:229], v[110:113]
	v_mfma_f32_16x16x32_bf16 v[94:97], v[148:151], v[234:237], v[94:97]
	v_mfma_f32_16x16x32_bf16 v[78:81], v[148:151], v[242:245], v[78:81]
	v_mfma_f32_16x16x32_bf16 v[74:77], v[182:185], v[242:245], v[74:77]
	v_mfma_f32_16x16x32_bf16 v[90:93], v[182:185], v[234:237], v[90:93]
	v_mfma_f32_16x16x32_bf16 v[106:109], v[182:185], v[226:229], v[106:109]
	v_mfma_f32_16x16x32_bf16 v[122:125], v[182:185], v[218:221], v[122:125]
	s_setprio 0
	s_setprio 1
	v_mfma_f32_16x16x32_bf16 v[114:117], v[186:189], v[214:217], v[114:117]
	v_mfma_f32_16x16x32_bf16 v[98:101], v[186:189], v[222:225], v[98:101]
	v_mfma_f32_16x16x32_bf16 v[82:85], v[186:189], v[230:233], v[82:85]
	v_mfma_f32_16x16x32_bf16 v[66:69], v[186:189], v[238:241], v[66:69]
	v_mfma_f32_16x16x32_bf16 v[70:73], v[194:197], v[238:241], v[70:73]
	v_mfma_f32_16x16x32_bf16 v[86:89], v[194:197], v[230:233], v[86:89]
	v_mfma_f32_16x16x32_bf16 v[102:105], v[194:197], v[222:225], v[102:105]
	v_mfma_f32_16x16x32_bf16 v[118:121], v[194:197], v[214:217], v[118:121]
	v_mfma_f32_16x16x32_bf16 v[114:117], v[190:193], v[218:221], v[114:117]
	v_mfma_f32_16x16x32_bf16 v[98:101], v[190:193], v[226:229], v[98:101]
	v_mfma_f32_16x16x32_bf16 v[82:85], v[190:193], v[234:237], v[82:85]
	v_mfma_f32_16x16x32_bf16 v[66:69], v[190:193], v[242:245], v[66:69]
	v_mfma_f32_16x16x32_bf16 v[70:73], v[210:213], v[242:245], v[70:73]
	v_mfma_f32_16x16x32_bf16 v[86:89], v[210:213], v[234:237], v[86:89]
	v_mfma_f32_16x16x32_bf16 v[102:105], v[210:213], v[226:229], v[102:105]
	v_mfma_f32_16x16x32_bf16 v[118:121], v[210:213], v[218:221], v[118:121]
	s_setprio 0
	s_barrier
	s_add_i32 s97, s97, s43
	v_lshl_add_u64 v[152:153], s[30:31], 0, v[136:137]
	s_mov_b32 m0, s97
	ds_read_b128 v[214:217], v177 offset:16384
	ds_read_b128 v[218:221], v177 offset:17408
	ds_read_b128 v[222:225], v177 offset:18432
	ds_read_b128 v[226:229], v177 offset:19456
	ds_read_b128 v[230:233], v177 offset:20480
	ds_read_b128 v[234:237], v177 offset:21504
	ds_read_b128 v[238:241], v177 offset:22528
	ds_read_b128 v[242:245], v177 offset:23552
	global_load_lds_dwordx4 v[152:153], off
	s_add_i32 m0, s97, 0x2000
	v_lshl_add_u64 v[198:199], s[30:31], 0, v[140:141]
	s_add_u32 s30, s30, s58
	s_addc_u32 s31, s31, 0
	s_add_i32 s97, vcc_lo, s43
	global_load_lds_dwordx4 v[198:199], off
	v_lshl_add_u64 v[200:201], s[30:31], 0, v[136:137]
	s_mov_b32 m0, s97
	v_lshl_add_u64 v[246:247], s[30:31], 0, v[140:141]
	global_load_lds_dwordx4 v[200:201], off
	s_add_i32 m0, s97, 0x2000
	v_lshl_add_u64 v[248:249], s[94:95], 0, v[134:135]
	global_load_lds_dwordx4 v[246:247], off
	s_mov_b32 m0, s36
	v_lshl_add_u64 v[250:251], s[94:95], 0, v[138:139]
	global_load_lds_dwordx4 v[248:249], off
	s_mov_b32 m0, s37
	s_nop 0
	global_load_lds_dwordx4 v[250:251], off
	s_waitcnt vmcnt(8)
	s_waitcnt lgkmcnt(0)
	s_barrier
; #define PG8_STAGE(bufoff, gbase, voff) do { _Pragma("unroll") for (int _i = 0; _i < 2; ++_i) \
;         __builtin_amdgcn_global_load_lds((const unsigned*)((const char*)(gbase) + (voff)[_i]), (LAS unsigned*)(lds + (bufoff) + ldsw + _i * 8192), 16, 0, 0); } while (0)
; #define PG8_LDA(dst, b, h) do { _Pragma("unroll") for (int m = 0; m < 4; ++m) _Pragma("unroll") for (int k = 0; k < 2; ++k) dst[m][k] = *(const LAS bf16x8*)(lds + PG8_SA(b, h) + aoff + m * 2048 + k * 1024); } while (0)
; #define PG8_LDB(dst, b, h) do { _Pragma("unroll") for (int n = 0; n < 2; ++n) _Pragma("unroll") for (int k = 0; k < 2; ++k) dst[n][k] = *(const LAS bf16x8*)(lds + PG8_SB(b, h) + boff + n * 2048 + k * 1024); } while (0)
; #define PG8_MMA(ai, bj, At, Bt) do { __builtin_amdgcn_s_setprio(1); _Pragma("unroll") for (int m = 0; m < 4; ++m) _Pragma("unroll") for (int n = 0; n < 2; ++n) _Pragma("unroll") for (int k = 0; k < 2; ++k) \
;         acc[ai][bj][m][n] = __builtin_amdgcn_mfma_f32_16x16x32_bf16(Bt[n][k], At[m][k], acc[ai][bj][m][n], 0, 0, 0); __builtin_amdgcn_s_setprio(0); } while (0)
; #define PG8_WAIT_V(n) asm volatile("s_waitcnt vmcnt(" #n ")" ::: "memory")
; #define PG8_WAIT_L(n) asm volatile("s_waitcnt lgkmcnt(" #n ")" ::: "memory")
; #define PG8_BAR __builtin_amdgcn_s_barrier()
; #define PG8_SCHED __builtin_amdgcn_sched_barrier(0)
; template <class Epi, class Sched>
; __device__ __forceinline__ void gemm_phase(LAS unsigned char* lds, const Gemm g, const Sched& S, const Epi& E, const int tid) {
;     ...
;             PG8_WAIT_V(8); PG8_WAIT_L(0); PG8_BAR; PG8_MMA(1, 0, At, B0); PG8_MMA(1, 1, At, B1); PG8_BAR; PG8_SCHED;
;             PG8_LDB(B0, 1, 0); PG8_LDB(B1, 1, 1); PG8_SCHED; PG8_LDA(At, 1, 0); PG8_STAGE(PG8_SA(0, 1), a2 + hstep, voffA);
;             PG8_WAIT_V(8); PG8_WAIT_L(0); PG8_BAR; PG8_MMA(0, 0, At, B0); PG8_MMA(0, 1, At, B1); PG8_BAR; PG8_SCHED;
	s_setprio 1
	s_waitcnt lgkmcnt(0)
	v_mfma_f32_16x16x32_bf16 v[62:65], v[130:133], v[214:217], v[62:65]
	v_mfma_f32_16x16x32_bf16 v[46:49], v[130:133], v[222:225], v[46:49]
	v_mfma_f32_16x16x32_bf16 v[30:33], v[130:133], v[230:233], v[30:33]
	v_mfma_f32_16x16x32_bf16 v[14:17], v[130:133], v[238:241], v[14:17]
	v_mfma_f32_16x16x32_bf16 v[10:13], v[178:181], v[238:241], v[10:13]
	v_mfma_f32_16x16x32_bf16 v[26:29], v[178:181], v[230:233], v[26:29]
	v_mfma_f32_16x16x32_bf16 v[42:45], v[178:181], v[222:225], v[42:45]
	v_mfma_f32_16x16x32_bf16 v[58:61], v[178:181], v[214:217], v[58:61]
	v_mfma_f32_16x16x32_bf16 v[62:65], v[148:151], v[218:221], v[62:65]
	v_mfma_f32_16x16x32_bf16 v[46:49], v[148:151], v[226:229], v[46:49]
	v_mfma_f32_16x16x32_bf16 v[30:33], v[148:151], v[234:237], v[30:33]
	v_mfma_f32_16x16x32_bf16 v[14:17], v[148:151], v[242:245], v[14:17]
	v_mfma_f32_16x16x32_bf16 v[10:13], v[182:185], v[242:245], v[10:13]
	v_mfma_f32_16x16x32_bf16 v[26:29], v[182:185], v[234:237], v[26:29]
	v_mfma_f32_16x16x32_bf16 v[42:45], v[182:185], v[226:229], v[42:45]
	v_mfma_f32_16x16x32_bf16 v[58:61], v[182:185], v[218:221], v[58:61]
	s_setprio 0
	s_setprio 1
	v_mfma_f32_16x16x32_bf16 v[50:53], v[186:189], v[214:217], v[50:53]
	v_mfma_f32_16x16x32_bf16 v[34:37], v[186:189], v[222:225], v[34:37]
	v_mfma_f32_16x16x32_bf16 v[18:21], v[186:189], v[230:233], v[18:21]
	v_mfma_f32_16x16x32_bf16 v[2:5], v[186:189], v[238:241], v[2:5]
	v_mfma_f32_16x16x32_bf16 v[6:9], v[194:197], v[238:241], v[6:9]
	v_mfma_f32_16x16x32_bf16 v[22:25], v[194:197], v[230:233], v[22:25]
	v_mfma_f32_16x16x32_bf16 v[38:41], v[194:197], v[222:225], v[38:41]
	v_mfma_f32_16x16x32_bf16 v[54:57], v[194:197], v[214:217], v[54:57]
	v_mfma_f32_16x16x32_bf16 v[50:53], v[190:193], v[218:221], v[50:53]
	v_mfma_f32_16x16x32_bf16 v[34:37], v[190:193], v[226:229], v[34:37]
	v_mfma_f32_16x16x32_bf16 v[18:21], v[190:193], v[234:237], v[18:21]
	v_mfma_f32_16x16x32_bf16 v[2:5], v[190:193], v[242:245], v[2:5]
	v_mfma_f32_16x16x32_bf16 v[6:9], v[210:213], v[242:245], v[6:9]
	v_mfma_f32_16x16x32_bf16 v[22:25], v[210:213], v[234:237], v[22:25]
	v_mfma_f32_16x16x32_bf16 v[38:41], v[210:213], v[226:229], v[38:41]
	v_mfma_f32_16x16x32_bf16 v[54:57], v[210:213], v[218:221], v[54:57]
	s_setprio 0
	s_barrier
	s_add_i32 s97, 0, 0x18000
	v_add_u32_e32 v0, s97, v175
	s_add_i32 vcc_lo, 0, 0x1c000
	ds_read_b128 v[130:133], v0
	ds_read_b128 v[148:151], v0 offset:1024
	ds_read_b128 v[178:181], v0 offset:2048
	ds_read_b128 v[182:185], v0 offset:3072
	v_add_u32_e32 v0, vcc_lo, v175
	ds_read_b128 v[186:189], v0
	ds_read_b128 v[190:193], v0 offset:1024
	ds_read_b128 v[194:197], v0 offset:2048
	ds_read_b128 v[210:213], v0 offset:3072
	s_add_u32 s30, s94, s58
	s_addc_u32 s31, s95, 0
	s_mov_b32 m0, s13
	v_lshl_add_u64 v[168:169], s[30:31], 0, v[134:135]
	ds_read_b128 v[214:217], v177 offset:32768
	ds_read_b128 v[218:221], v177 offset:33792
	ds_read_b128 v[222:225], v177 offset:34816
	ds_read_b128 v[226:229], v177 offset:35840
	ds_read_b128 v[230:233], v177 offset:36864
	ds_read_b128 v[234:237], v177 offset:37888
	ds_read_b128 v[238:241], v177 offset:38912
	ds_read_b128 v[242:245], v177 offset:39936
	global_load_lds_dwordx4 v[168:169], off
	v_lshl_add_u64 v[168:169], s[30:31], 0, v[138:139]
	s_mov_b32 m0, s26
	s_nop 0
	global_load_lds_dwordx4 v[168:169], off
	s_waitcnt vmcnt(8)
	s_waitcnt lgkmcnt(0)
	s_barrier
	s_setprio 1
	s_waitcnt lgkmcnt(0)
	v_mfma_f32_16x16x32_bf16 v[126:129], v[130:133], v[214:217], v[126:129]
	v_mfma_f32_16x16x32_bf16 v[110:113], v[130:133], v[222:225], v[110:113]
	v_mfma_f32_16x16x32_bf16 v[94:97], v[130:133], v[230:233], v[94:97]
	v_mfma_f32_16x16x32_bf16 v[78:81], v[130:133], v[238:241], v[78:81]
	v_mfma_f32_16x16x32_bf16 v[74:77], v[178:181], v[238:241], v[74:77]
	v_mfma_f32_16x16x32_bf16 v[90:93], v[178:181], v[230:233], v[90:93]
	v_mfma_f32_16x16x32_bf16 v[106:109], v[178:181], v[222:225], v[106:109]
	v_mfma_f32_16x16x32_bf16 v[122:125], v[178:181], v[214:217], v[122:125]
	v_mfma_f32_16x16x32_bf16 v[126:129], v[148:151], v[218:221], v[126:129]
	v_mfma_f32_16x16x32_bf16 v[110:113], v[148:151], v[226:229], v[110:113]
	v_mfma_f32_16x16x32_bf16 v[94:97], v[148:151], v[234:237], v[94:97]
	v_mfma_f32_16x16x32_bf16 v[78:81], v[148:151], v[242:245], v[78:81]
	v_mfma_f32_16x16x32_bf16 v[74:77], v[182:185], v[242:245], v[74:77]
	v_mfma_f32_16x16x32_bf16 v[90:93], v[182:185], v[234:237], v[90:93]
	v_mfma_f32_16x16x32_bf16 v[106:109], v[182:185], v[226:229], v[106:109]
	v_mfma_f32_16x16x32_bf16 v[122:125], v[182:185], v[218:221], v[122:125]
	s_setprio 0
	s_setprio 1
	v_mfma_f32_16x16x32_bf16 v[114:117], v[186:189], v[214:217], v[114:117]
	v_mfma_f32_16x16x32_bf16 v[98:101], v[186:189], v[222:225], v[98:101]
	v_mfma_f32_16x16x32_bf16 v[82:85], v[186:189], v[230:233], v[82:85]
	v_mfma_f32_16x16x32_bf16 v[66:69], v[186:189], v[238:241], v[66:69]
	v_mfma_f32_16x16x32_bf16 v[70:73], v[194:197], v[238:241], v[70:73]
	v_mfma_f32_16x16x32_bf16 v[86:89], v[194:197], v[230:233], v[86:89]
	v_mfma_f32_16x16x32_bf16 v[102:105], v[194:197], v[222:225], v[102:105]
	v_mfma_f32_16x16x32_bf16 v[118:121], v[194:197], v[214:217], v[118:121]
	v_mfma_f32_16x16x32_bf16 v[114:117], v[190:193], v[218:221], v[114:117]
	v_mfma_f32_16x16x32_bf16 v[98:101], v[190:193], v[226:229], v[98:101]
	v_mfma_f32_16x16x32_bf16 v[82:85], v[190:193], v[234:237], v[82:85]
	v_mfma_f32_16x16x32_bf16 v[66:69], v[190:193], v[242:245], v[66:69]
	v_mfma_f32_16x16x32_bf16 v[70:73], v[210:213], v[242:245], v[70:73]
	v_mfma_f32_16x16x32_bf16 v[86:89], v[210:213], v[234:237], v[86:89]
	v_mfma_f32_16x16x32_bf16 v[102:105], v[210:213], v[226:229], v[102:105]
	v_mfma_f32_16x16x32_bf16 v[118:121], v[210:213], v[218:221], v[118:121]
	s_setprio 0
	s_barrier
; #define PG8_STAGE(bufoff, gbase, voff) do { _Pragma("unroll") for (int _i = 0; _i < 2; ++_i) \
;         __builtin_amdgcn_global_load_lds((const unsigned*)((const char*)(gbase) + (voff)[_i]), (LAS unsigned*)(lds + (bufoff) + ldsw + _i * 8192), 16, 0, 0); } while (0)
; #define PG8_LDA(dst, b, h) do { _Pragma("unroll") for (int m = 0; m < 4; ++m) _Pragma("unroll") for (int k = 0; k < 2; ++k) dst[m][k] = *(const LAS bf16x8*)(lds + PG8_SA(b, h) + aoff + m * 2048 + k * 1024); } while (0)
; #define PG8_MMA(ai, bj, At, Bt) do { __builtin_amdgcn_s_setprio(1); _Pragma("unroll") for (int m = 0; m < 4; ++m) _Pragma("unroll") for (int n = 0; n < 2; ++n) _Pragma("unroll") for (int k = 0; k < 2; ++k) \
;         acc[ai][bj][m][n] = __builtin_amdgcn_mfma_f32_16x16x32_bf16(Bt[n][k], At[m][k], acc[ai][bj][m][n], 0, 0, 0); __builtin_amdgcn_s_setprio(0); } while (0)
; #define PG8_WAIT_V(n) asm volatile("s_waitcnt vmcnt(" #n ")" ::: "memory")
; #define PG8_WAIT_L(n) asm volatile("s_waitcnt lgkmcnt(" #n ")" ::: "memory")
; #define PG8_BAR __builtin_amdgcn_s_barrier()
; #define PG8_SCHED __builtin_amdgcn_sched_barrier(0)
; template <class Epi, class Sched>
; __device__ __forceinline__ void gemm_phase(LAS unsigned char* lds, const Gemm g, const Sched& S, const Epi& E, const int tid) {
;     ...
;             PG8_LDA(At, 1, 1); PG8_STAGE(PG8_SB(1, 0), b3, voffB); PG8_STAGE(PG8_SB(1, 1), b3 + hstep, voffB); PG8_STAGE(PG8_SA(1, 0), a3, voffA);
;             PG8_WAIT_V(8); PG8_WAIT_L(0); PG8_BAR; PG8_MMA(1, 0, At, B0); PG8_MMA(1, 1, At, B1); PG8_BAR; PG8_SCHED;
;         }
	s_add_i32 s30, s97, s43
	v_lshl_add_u64 v[152:153], v[152:153], 0, s[74:75]
	s_mov_b32 m0, s30
	ds_read_b128 v[214:217], v177 offset:49152
	ds_read_b128 v[218:221], v177 offset:50176
	ds_read_b128 v[222:225], v177 offset:51200
	ds_read_b128 v[226:229], v177 offset:52224
	ds_read_b128 v[230:233], v177 offset:53248
	ds_read_b128 v[234:237], v177 offset:54272
	ds_read_b128 v[238:241], v177 offset:55296
	ds_read_b128 v[242:245], v177 offset:56320
	global_load_lds_dwordx4 v[152:153], off
	v_lshl_add_u64 v[152:153], v[198:199], 0, s[74:75]
	s_add_i32 m0, s30, 0x2000
	s_add_i32 s30, vcc_lo, s43
	global_load_lds_dwordx4 v[152:153], off
	v_lshl_add_u64 v[152:153], v[200:201], 0, s[74:75]
	s_mov_b32 m0, s30
	s_nop 0
	global_load_lds_dwordx4 v[152:153], off
	v_lshl_add_u64 v[152:153], v[246:247], 0, s[74:75]
	s_add_i32 m0, s30, 0x2000
	s_nop 0
	global_load_lds_dwordx4 v[152:153], off
	v_lshl_add_u64 v[152:153], v[248:249], 0, s[74:75]
	s_mov_b32 m0, s25
	s_nop 0
	global_load_lds_dwordx4 v[152:153], off
	v_lshl_add_u64 v[152:153], v[250:251], 0, s[74:75]
	s_mov_b32 m0, s18
	s_nop 0
	global_load_lds_dwordx4 v[152:153], off
	s_waitcnt vmcnt(8)
	s_waitcnt lgkmcnt(0)
	s_barrier
	s_setprio 1
	s_waitcnt lgkmcnt(0)
	v_mfma_f32_16x16x32_bf16 v[62:65], v[130:133], v[214:217], v[62:65]
	v_mfma_f32_16x16x32_bf16 v[46:49], v[130:133], v[222:225], v[46:49]
	v_mfma_f32_16x16x32_bf16 v[30:33], v[130:133], v[230:233], v[30:33]
	v_mfma_f32_16x16x32_bf16 v[14:17], v[130:133], v[238:241], v[14:17]
	v_mfma_f32_16x16x32_bf16 v[10:13], v[178:181], v[238:241], v[10:13]
	v_mfma_f32_16x16x32_bf16 v[26:29], v[178:181], v[230:233], v[26:29]
	v_mfma_f32_16x16x32_bf16 v[42:45], v[178:181], v[222:225], v[42:45]
	v_mfma_f32_16x16x32_bf16 v[58:61], v[178:181], v[214:217], v[58:61]
	v_mfma_f32_16x16x32_bf16 v[62:65], v[148:151], v[218:221], v[62:65]
	v_mfma_f32_16x16x32_bf16 v[46:49], v[148:151], v[226:229], v[46:49]
	v_mfma_f32_16x16x32_bf16 v[30:33], v[148:151], v[234:237], v[30:33]
	v_mfma_f32_16x16x32_bf16 v[14:17], v[148:151], v[242:245], v[14:17]
	v_mfma_f32_16x16x32_bf16 v[10:13], v[182:185], v[242:245], v[10:13]
	v_mfma_f32_16x16x32_bf16 v[26:29], v[182:185], v[234:237], v[26:29]
	v_mfma_f32_16x16x32_bf16 v[42:45], v[182:185], v[226:229], v[42:45]
	v_mfma_f32_16x16x32_bf16 v[58:61], v[182:185], v[218:221], v[58:61]
	s_setprio 0
	s_setprio 1
	v_mfma_f32_16x16x32_bf16 v[50:53], v[186:189], v[214:217], v[50:53]
	v_mfma_f32_16x16x32_bf16 v[34:37], v[186:189], v[222:225], v[34:37]
	v_mfma_f32_16x16x32_bf16 v[18:21], v[186:189], v[230:233], v[18:21]
	v_mfma_f32_16x16x32_bf16 v[2:5], v[186:189], v[238:241], v[2:5]
	v_mfma_f32_16x16x32_bf16 v[6:9], v[194:197], v[238:241], v[6:9]
	v_mfma_f32_16x16x32_bf16 v[22:25], v[194:197], v[230:233], v[22:25]
	v_mfma_f32_16x16x32_bf16 v[38:41], v[194:197], v[222:225], v[38:41]
	v_mfma_f32_16x16x32_bf16 v[54:57], v[194:197], v[214:217], v[54:57]
	v_mfma_f32_16x16x32_bf16 v[50:53], v[190:193], v[218:221], v[50:53]
	v_mfma_f32_16x16x32_bf16 v[34:37], v[190:193], v[226:229], v[34:37]
	v_mfma_f32_16x16x32_bf16 v[18:21], v[190:193], v[234:237], v[18:21]
	v_mfma_f32_16x16x32_bf16 v[2:5], v[190:193], v[242:245], v[2:5]
	v_mfma_f32_16x16x32_bf16 v[6:9], v[210:213], v[242:245], v[6:9]
	v_mfma_f32_16x16x32_bf16 v[22:25], v[210:213], v[234:237], v[22:25]
	v_mfma_f32_16x16x32_bf16 v[38:41], v[210:213], v[226:229], v[38:41]
	v_mfma_f32_16x16x32_bf16 v[54:57], v[210:213], v[218:221], v[54:57]
	s_setprio 0
	s_barrier
	s_add_u32 s98, s98, 0x100
	s_addc_u32 s99, s99, 0
	s_add_u32 s0, s0, 0x100
	s_addc_u32 s1, s1, 0
	s_cmp_ge_u32 s96, s24
	s_mov_b32 s31, s96
	s_cbranch_scc0 .LBB0_417
	s_and_b64 vcc, exec, s[66:67]
	s_cbranch_vccz .LBB0_420
	s_barrier

; #define PG8_STAGE(bufoff, gbase, voff) do { _Pragma("unroll") for (int _i = 0; _i < 2; ++_i) \
;         __builtin_amdgcn_global_load_lds((const unsigned*)((const char*)(gbase) + (voff)[_i]), (LAS unsigned*)(lds + (bufoff) + ldsw + _i * 8192), 16, 0, 0); } while (0)
; #define PG8_LDA(dst, b, h) do { _Pragma("unroll") for (int m = 0; m < 4; ++m) _Pragma("unroll") for (int k = 0; k < 2; ++k) dst[m][k] = *(const LAS bf16x8*)(lds + PG8_SA(b, h) + aoff + m * 2048 + k * 1024); } while (0)
; #define PG8_LDB(dst, b, h) do { _Pragma("unroll") for (int n = 0; n < 2; ++n) _Pragma("unroll") for (int k = 0; k < 2; ++k) dst[n][k] = *(const LAS bf16x8*)(lds + PG8_SB(b, h) + boff + n * 2048 + k * 1024); } while (0)
; #define PG8_MMA(ai, bj, At, Bt) do { __builtin_amdgcn_s_setprio(1); _Pragma("unroll") for (int m = 0; m < 4; ++m) _Pragma("unroll") for (int n = 0; n < 2; ++n) _Pragma("unroll") for (int k = 0; k < 2; ++k) \
;         acc[ai][bj][m][n] = __builtin_amdgcn_mfma_f32_16x16x32_bf16(Bt[n][k], At[m][k], acc[ai][bj][m][n], 0, 0, 0); __builtin_amdgcn_s_setprio(0); } while (0)
; #define PG8_WAIT_V(n) asm volatile("s_waitcnt vmcnt(" #n ")" ::: "memory")
; #define PG8_WAIT_L(n) asm volatile("s_waitcnt lgkmcnt(" #n ")" ::: "memory")
; #define PG8_BAR __builtin_amdgcn_s_barrier()
; #define PG8_SCHED __builtin_amdgcn_sched_barrier(0)
; template <class Epi, class Sched>
; __device__ __forceinline__ void gemm_phase(LAS unsigned char* lds, const Gemm g, const Sched& S, const Epi& E, const int tid) {
;     ...
;         for (int t = 0; t < nt; t += 2) {
;             const bool last = (t == nt - 2);
;             const char* a1 = cA + (size_t)(t + 1) * kstep;
;             const char* a2 = last ? nA : cA + (size_t)(t + 2) * kstep; const char* b2 = last ? nB : cB + (size_t)(t + 2) * kstep;
;             const char* a3 = a2 + kstep; const char* b3 = b2 + kstep;
;             PG8_LDB(B0, 0, 0); PG8_LDB(B1, 0, 1); PG8_SCHED; PG8_LDA(At, 0, 0); PG8_STAGE(PG8_SA(1, 1), a1 + hstep, voffA);
;             PG8_WAIT_V(8); PG8_WAIT_L(0); PG8_BAR; PG8_MMA(0, 0, At, B0); PG8_MMA(0, 1, At, B1); PG8_BAR; PG8_SCHED;
;             PG8_LDA(At, 0, 1); PG8_STAGE(PG8_SB(0, 0), b2, voffB); PG8_STAGE(PG8_SB(0, 1), b2 + hstep, voffB); PG8_STAGE(PG8_SA(0, 0), a2, voffA);
.LBB0_480:
	s_add_i32 s66, s31, 2
	s_add_u32 s30, s62, 0x80
	s_addc_u32 s64, s63, 0
	s_add_i32 s67, 0, 0x10000
	s_cmp_eq_u32 s36, s31
	s_cselect_b32 s65, s5, s64
	s_cselect_b32 s64, s4, s30
	v_add_u32_e32 v152, s67, v141
	s_cselect_b32 s31, s61, s43
	s_cselect_b32 s30, s60, s42
	s_add_i32 s68, 0, 0x14000
	ds_read_b128 v[144:147], v152
	ds_read_b128 v[148:151], v152 offset:1024
	ds_read_b128 v[174:177], v152 offset:2048
	ds_read_b128 v[178:181], v152 offset:3072
	v_add_u32_e32 v152, s68, v141
	ds_read_b128 v[182:185], v152
	ds_read_b128 v[186:189], v152 offset:1024
	ds_read_b128 v[190:193], v152 offset:2048
	ds_read_b128 v[194:197], v152 offset:3072
	v_lshl_add_u64 v[152:153], s[62:63], 0, v[138:139]
	s_add_i32 m0, s23, 0xc000
	ds_read_b128 v[210:213], v143
	ds_read_b128 v[214:217], v143 offset:1024
	ds_read_b128 v[218:221], v143 offset:2048
	ds_read_b128 v[222:225], v143 offset:3072
	ds_read_b128 v[226:229], v143 offset:4096
	ds_read_b128 v[230:233], v143 offset:5120
	ds_read_b128 v[234:237], v143 offset:6144
	ds_read_b128 v[238:241], v143 offset:7168
	global_load_lds_dwordx4 v[152:153], off
	v_lshl_add_u64 v[152:153], s[62:63], 0, v[136:137]
	s_add_i32 m0, s23, 0xe000
	s_nop 0
	global_load_lds_dwordx4 v[152:153], off
	s_waitcnt vmcnt(8)
	s_waitcnt lgkmcnt(0)
	s_barrier
	s_setprio 1
	s_waitcnt lgkmcnt(0)
	v_mfma_f32_16x16x32_bf16 v[126:129], v[144:147], v[210:213], v[126:129]
	v_mfma_f32_16x16x32_bf16 v[118:121], v[144:147], v[218:221], v[118:121]
	v_mfma_f32_16x16x32_bf16 v[102:105], v[144:147], v[226:229], v[102:105]
	v_mfma_f32_16x16x32_bf16 v[86:89], v[144:147], v[234:237], v[86:89]
	v_mfma_f32_16x16x32_bf16 v[82:85], v[174:177], v[234:237], v[82:85]
	v_mfma_f32_16x16x32_bf16 v[98:101], v[174:177], v[226:229], v[98:101]
	v_mfma_f32_16x16x32_bf16 v[114:117], v[174:177], v[218:221], v[114:117]
	v_mfma_f32_16x16x32_bf16 v[122:125], v[174:177], v[210:213], v[122:125]
	v_mfma_f32_16x16x32_bf16 v[126:129], v[148:151], v[214:217], v[126:129]
	v_mfma_f32_16x16x32_bf16 v[118:121], v[148:151], v[222:225], v[118:121]
	v_mfma_f32_16x16x32_bf16 v[102:105], v[148:151], v[230:233], v[102:105]
	v_mfma_f32_16x16x32_bf16 v[86:89], v[148:151], v[238:241], v[86:89]
	v_mfma_f32_16x16x32_bf16 v[82:85], v[178:181], v[238:241], v[82:85]
	v_mfma_f32_16x16x32_bf16 v[98:101], v[178:181], v[230:233], v[98:101]
	v_mfma_f32_16x16x32_bf16 v[114:117], v[178:181], v[222:225], v[114:117]
	v_mfma_f32_16x16x32_bf16 v[122:125], v[178:181], v[214:217], v[122:125]
	s_setprio 0
	s_setprio 1
	v_mfma_f32_16x16x32_bf16 v[110:113], v[182:185], v[210:213], v[110:113]
	v_mfma_f32_16x16x32_bf16 v[94:97], v[182:185], v[218:221], v[94:97]
	v_mfma_f32_16x16x32_bf16 v[78:81], v[182:185], v[226:229], v[78:81]
	v_mfma_f32_16x16x32_bf16 v[70:73], v[182:185], v[234:237], v[70:73]
	v_mfma_f32_16x16x32_bf16 v[66:69], v[190:193], v[234:237], v[66:69]
	v_mfma_f32_16x16x32_bf16 v[74:77], v[190:193], v[226:229], v[74:77]
	v_mfma_f32_16x16x32_bf16 v[90:93], v[190:193], v[218:221], v[90:93]
	v_mfma_f32_16x16x32_bf16 v[106:109], v[190:193], v[210:213], v[106:109]
	v_mfma_f32_16x16x32_bf16 v[110:113], v[186:189], v[214:217], v[110:113]
	v_mfma_f32_16x16x32_bf16 v[94:97], v[186:189], v[222:225], v[94:97]
	v_mfma_f32_16x16x32_bf16 v[78:81], v[186:189], v[230:233], v[78:81]
	v_mfma_f32_16x16x32_bf16 v[70:73], v[186:189], v[238:241], v[70:73]
	v_mfma_f32_16x16x32_bf16 v[66:69], v[194:197], v[238:241], v[66:69]
	v_mfma_f32_16x16x32_bf16 v[74:77], v[194:197], v[230:233], v[74:77]
	v_mfma_f32_16x16x32_bf16 v[90:93], v[194:197], v[222:225], v[90:93]
	v_mfma_f32_16x16x32_bf16 v[106:109], v[194:197], v[214:217], v[106:109]
	s_setprio 0
	s_barrier
	s_add_i32 s67, s67, s20
	v_lshl_add_u64 v[152:153], s[30:31], 0, v[0:1]
	s_mov_b32 m0, s67
	ds_read_b128 v[210:213], v143 offset:16384
	ds_read_b128 v[214:217], v143 offset:17408
	ds_read_b128 v[218:221], v143 offset:18432
	ds_read_b128 v[222:225], v143 offset:19456
	ds_read_b128 v[226:229], v143 offset:20480
	ds_read_b128 v[230:233], v143 offset:21504
	ds_read_b128 v[234:237], v143 offset:22528
	ds_read_b128 v[238:241], v143 offset:23552
	global_load_lds_dwordx4 v[152:153], off
	s_add_i32 m0, s67, 0x2000
	v_lshl_add_u64 v[198:199], s[30:31], 0, v[134:135]
	s_add_u32 s30, s30, s2
	s_addc_u32 s31, s31, 0
	s_add_i32 s67, s68, s20
	global_load_lds_dwordx4 v[198:199], off
	v_lshl_add_u64 v[200:201], s[30:31], 0, v[0:1]
	s_mov_b32 m0, s67
	v_lshl_add_u64 v[242:243], s[30:31], 0, v[134:135]
	global_load_lds_dwordx4 v[200:201], off
	s_add_i32 m0, s67, 0x2000
	v_lshl_add_u64 v[244:245], s[64:65], 0, v[130:131]
	global_load_lds_dwordx4 v[242:243], off
	s_mov_b32 m0, s23
	v_lshl_add_u64 v[246:247], s[64:65], 0, v[132:133]
	global_load_lds_dwordx4 v[244:245], off
	s_mov_b32 m0, s24
	s_nop 0
	global_load_lds_dwordx4 v[246:247], off
	s_waitcnt vmcnt(8)
	s_waitcnt lgkmcnt(0)
	s_barrier
; #define PG8_STAGE(bufoff, gbase, voff) do { _Pragma("unroll") for (int _i = 0; _i < 2; ++_i) \
;         __builtin_amdgcn_global_load_lds((const unsigned*)((const char*)(gbase) + (voff)[_i]), (LAS unsigned*)(lds + (bufoff) + ldsw + _i * 8192), 16, 0, 0); } while (0)
; #define PG8_LDA(dst, b, h) do { _Pragma("unroll") for (int m = 0; m < 4; ++m) _Pragma("unroll") for (int k = 0; k < 2; ++k) dst[m][k] = *(const LAS bf16x8*)(lds + PG8_SA(b, h) + aoff + m * 2048 + k * 1024); } while (0)
; #define PG8_LDB(dst, b, h) do { _Pragma("unroll") for (int n = 0; n < 2; ++n) _Pragma("unroll") for (int k = 0; k < 2; ++k) dst[n][k] = *(const LAS bf16x8*)(lds + PG8_SB(b, h) + boff + n * 2048 + k * 1024); } while (0)
; #define PG8_MMA(ai, bj, At, Bt) do { __builtin_amdgcn_s_setprio(1); _Pragma("unroll") for (int m = 0; m < 4; ++m) _Pragma("unroll") for (int n = 0; n < 2; ++n) _Pragma("unroll") for (int k = 0; k < 2; ++k) \
;         acc[ai][bj][m][n] = __builtin_amdgcn_mfma_f32_16x16x32_bf16(Bt[n][k], At[m][k], acc[ai][bj][m][n], 0, 0, 0); __builtin_amdgcn_s_setprio(0); } while (0)
; #define PG8_WAIT_V(n) asm volatile("s_waitcnt vmcnt(" #n ")" ::: "memory")
; #define PG8_WAIT_L(n) asm volatile("s_waitcnt lgkmcnt(" #n ")" ::: "memory")
; #define PG8_BAR __builtin_amdgcn_s_barrier()
; #define PG8_SCHED __builtin_amdgcn_sched_barrier(0)
; template <class Epi, class Sched>
; __device__ __forceinline__ void gemm_phase(LAS unsigned char* lds, const Gemm g, const Sched& S, const Epi& E, const int tid) {
;     ...
;             PG8_WAIT_V(8); PG8_WAIT_L(0); PG8_BAR; PG8_MMA(1, 0, At, B0); PG8_MMA(1, 1, At, B1); PG8_BAR; PG8_SCHED;
;             PG8_LDB(B0, 1, 0); PG8_LDB(B1, 1, 1); PG8_SCHED; PG8_LDA(At, 1, 0); PG8_STAGE(PG8_SA(0, 1), a2 + hstep, voffA);
;             PG8_WAIT_V(8); PG8_WAIT_L(0); PG8_BAR; PG8_MMA(0, 0, At, B0); PG8_MMA(0, 1, At, B1); PG8_BAR; PG8_SCHED;
	s_setprio 1
	s_waitcnt lgkmcnt(0)
	v_mfma_f32_16x16x32_bf16 v[62:65], v[144:147], v[210:213], v[62:65]
	v_mfma_f32_16x16x32_bf16 v[54:57], v[144:147], v[218:221], v[54:57]
	v_mfma_f32_16x16x32_bf16 v[38:41], v[144:147], v[226:229], v[38:41]
	v_mfma_f32_16x16x32_bf16 v[22:25], v[144:147], v[234:237], v[22:25]
	v_mfma_f32_16x16x32_bf16 v[14:17], v[174:177], v[234:237], v[14:17]
	v_mfma_f32_16x16x32_bf16 v[30:33], v[174:177], v[226:229], v[30:33]
	v_mfma_f32_16x16x32_bf16 v[46:49], v[174:177], v[218:221], v[46:49]
	v_mfma_f32_16x16x32_bf16 v[58:61], v[174:177], v[210:213], v[58:61]
	v_mfma_f32_16x16x32_bf16 v[62:65], v[148:151], v[214:217], v[62:65]
	v_mfma_f32_16x16x32_bf16 v[54:57], v[148:151], v[222:225], v[54:57]
	v_mfma_f32_16x16x32_bf16 v[38:41], v[148:151], v[230:233], v[38:41]
	v_mfma_f32_16x16x32_bf16 v[22:25], v[148:151], v[238:241], v[22:25]
	v_mfma_f32_16x16x32_bf16 v[14:17], v[178:181], v[238:241], v[14:17]
	v_mfma_f32_16x16x32_bf16 v[30:33], v[178:181], v[230:233], v[30:33]
	v_mfma_f32_16x16x32_bf16 v[46:49], v[178:181], v[222:225], v[46:49]
	v_mfma_f32_16x16x32_bf16 v[58:61], v[178:181], v[214:217], v[58:61]
	s_setprio 0
	s_setprio 1
	v_mfma_f32_16x16x32_bf16 v[50:53], v[182:185], v[210:213], v[50:53]
	v_mfma_f32_16x16x32_bf16 v[34:37], v[182:185], v[218:221], v[34:37]
	v_mfma_f32_16x16x32_bf16 v[18:21], v[182:185], v[226:229], v[18:21]
	v_mfma_f32_16x16x32_bf16 v[6:9], v[182:185], v[234:237], v[6:9]
	v_mfma_f32_16x16x32_bf16 v[2:5], v[190:193], v[234:237], v[2:5]
	v_mfma_f32_16x16x32_bf16 v[10:13], v[190:193], v[226:229], v[10:13]
	v_mfma_f32_16x16x32_bf16 v[26:29], v[190:193], v[218:221], v[26:29]
	v_mfma_f32_16x16x32_bf16 v[42:45], v[190:193], v[210:213], v[42:45]
	v_mfma_f32_16x16x32_bf16 v[50:53], v[186:189], v[214:217], v[50:53]
	v_mfma_f32_16x16x32_bf16 v[34:37], v[186:189], v[222:225], v[34:37]
	v_mfma_f32_16x16x32_bf16 v[18:21], v[186:189], v[230:233], v[18:21]
	v_mfma_f32_16x16x32_bf16 v[6:9], v[186:189], v[238:241], v[6:9]
	v_mfma_f32_16x16x32_bf16 v[2:5], v[194:197], v[238:241], v[2:5]
	v_mfma_f32_16x16x32_bf16 v[10:13], v[194:197], v[230:233], v[10:13]
	v_mfma_f32_16x16x32_bf16 v[26:29], v[194:197], v[222:225], v[26:29]
	v_mfma_f32_16x16x32_bf16 v[42:45], v[194:197], v[214:217], v[42:45]
	s_setprio 0
	s_barrier
	s_add_i32 s67, 0, 0x18000
	v_add_u32_e32 v168, s67, v141
	s_add_i32 s68, 0, 0x1c000
	ds_read_b128 v[144:147], v168
	ds_read_b128 v[148:151], v168 offset:1024
	ds_read_b128 v[174:177], v168 offset:2048
	ds_read_b128 v[178:181], v168 offset:3072
	v_add_u32_e32 v168, s68, v141
	ds_read_b128 v[182:185], v168
	ds_read_b128 v[186:189], v168 offset:1024
	ds_read_b128 v[190:193], v168 offset:2048
	ds_read_b128 v[194:197], v168 offset:3072
	s_add_u32 s30, s64, s2
	s_addc_u32 s31, s65, 0
	s_mov_b32 m0, s25
	v_lshl_add_u64 v[248:249], s[30:31], 0, v[130:131]
	ds_read_b128 v[210:213], v143 offset:32768
	ds_read_b128 v[214:217], v143 offset:33792
	ds_read_b128 v[218:221], v143 offset:34816
	ds_read_b128 v[222:225], v143 offset:35840
	ds_read_b128 v[226:229], v143 offset:36864
	ds_read_b128 v[230:233], v143 offset:37888
	ds_read_b128 v[234:237], v143 offset:38912
	ds_read_b128 v[238:241], v143 offset:39936
	global_load_lds_dwordx4 v[248:249], off
	v_lshl_add_u64 v[248:249], s[30:31], 0, v[132:133]
	s_mov_b32 m0, s26
	s_nop 0
	global_load_lds_dwordx4 v[248:249], off
	s_waitcnt vmcnt(8)
	s_waitcnt lgkmcnt(0)
	s_barrier
	s_setprio 1
	s_waitcnt lgkmcnt(0)
	v_mfma_f32_16x16x32_bf16 v[126:129], v[144:147], v[210:213], v[126:129]
	v_mfma_f32_16x16x32_bf16 v[118:121], v[144:147], v[218:221], v[118:121]
	v_mfma_f32_16x16x32_bf16 v[102:105], v[144:147], v[226:229], v[102:105]
	v_mfma_f32_16x16x32_bf16 v[86:89], v[144:147], v[234:237], v[86:89]
	v_mfma_f32_16x16x32_bf16 v[82:85], v[174:177], v[234:237], v[82:85]
	v_mfma_f32_16x16x32_bf16 v[98:101], v[174:177], v[226:229], v[98:101]
	v_mfma_f32_16x16x32_bf16 v[114:117], v[174:177], v[218:221], v[114:117]
	v_mfma_f32_16x16x32_bf16 v[122:125], v[174:177], v[210:213], v[122:125]
	v_mfma_f32_16x16x32_bf16 v[126:129], v[148:151], v[214:217], v[126:129]
	v_mfma_f32_16x16x32_bf16 v[118:121], v[148:151], v[222:225], v[118:121]
	v_mfma_f32_16x16x32_bf16 v[102:105], v[148:151], v[230:233], v[102:105]
	v_mfma_f32_16x16x32_bf16 v[86:89], v[148:151], v[238:241], v[86:89]
	v_mfma_f32_16x16x32_bf16 v[82:85], v[178:181], v[238:241], v[82:85]
	v_mfma_f32_16x16x32_bf16 v[98:101], v[178:181], v[230:233], v[98:101]
	v_mfma_f32_16x16x32_bf16 v[114:117], v[178:181], v[222:225], v[114:117]
	v_mfma_f32_16x16x32_bf16 v[122:125], v[178:181], v[214:217], v[122:125]
	s_setprio 0
	s_setprio 1
	v_mfma_f32_16x16x32_bf16 v[110:113], v[182:185], v[210:213], v[110:113]
	v_mfma_f32_16x16x32_bf16 v[94:97], v[182:185], v[218:221], v[94:97]
	v_mfma_f32_16x16x32_bf16 v[78:81], v[182:185], v[226:229], v[78:81]
	v_mfma_f32_16x16x32_bf16 v[70:73], v[182:185], v[234:237], v[70:73]
	v_mfma_f32_16x16x32_bf16 v[66:69], v[190:193], v[234:237], v[66:69]
	v_mfma_f32_16x16x32_bf16 v[74:77], v[190:193], v[226:229], v[74:77]
	v_mfma_f32_16x16x32_bf16 v[90:93], v[190:193], v[218:221], v[90:93]
	v_mfma_f32_16x16x32_bf16 v[106:109], v[190:193], v[210:213], v[106:109]
	v_mfma_f32_16x16x32_bf16 v[110:113], v[186:189], v[214:217], v[110:113]
	v_mfma_f32_16x16x32_bf16 v[94:97], v[186:189], v[222:225], v[94:97]
	v_mfma_f32_16x16x32_bf16 v[78:81], v[186:189], v[230:233], v[78:81]
	v_mfma_f32_16x16x32_bf16 v[70:73], v[186:189], v[238:241], v[70:73]
	v_mfma_f32_16x16x32_bf16 v[66:69], v[194:197], v[238:241], v[66:69]
	v_mfma_f32_16x16x32_bf16 v[74:77], v[194:197], v[230:233], v[74:77]
	v_mfma_f32_16x16x32_bf16 v[90:93], v[194:197], v[222:225], v[90:93]
	v_mfma_f32_16x16x32_bf16 v[106:109], v[194:197], v[214:217], v[106:109]
	s_setprio 0
	s_barrier
; #define PG8_STAGE(bufoff, gbase, voff) do { _Pragma("unroll") for (int _i = 0; _i < 2; ++_i) \
;         __builtin_amdgcn_global_load_lds((const unsigned*)((const char*)(gbase) + (voff)[_i]), (LAS unsigned*)(lds + (bufoff) + ldsw + _i * 8192), 16, 0, 0); } while (0)
; #define PG8_LDA(dst, b, h) do { _Pragma("unroll") for (int m = 0; m < 4; ++m) _Pragma("unroll") for (int k = 0; k < 2; ++k) dst[m][k] = *(const LAS bf16x8*)(lds + PG8_SA(b, h) + aoff + m * 2048 + k * 1024); } while (0)
; #define PG8_MMA(ai, bj, At, Bt) do { __builtin_amdgcn_s_setprio(1); _Pragma("unroll") for (int m = 0; m < 4; ++m) _Pragma("unroll") for (int n = 0; n < 2; ++n) _Pragma("unroll") for (int k = 0; k < 2; ++k) \
;         acc[ai][bj][m][n] = __builtin_amdgcn_mfma_f32_16x16x32_bf16(Bt[n][k], At[m][k], acc[ai][bj][m][n], 0, 0, 0); __builtin_amdgcn_s_setprio(0); } while (0)
; #define PG8_WAIT_V(n) asm volatile("s_waitcnt vmcnt(" #n ")" ::: "memory")
; #define PG8_WAIT_L(n) asm volatile("s_waitcnt lgkmcnt(" #n ")" ::: "memory")
; #define PG8_BAR __builtin_amdgcn_s_barrier()
; #define PG8_SCHED __builtin_amdgcn_sched_barrier(0)
; template <class Epi, class Sched>
; __device__ __forceinline__ void gemm_phase(LAS unsigned char* lds, const Gemm g, const Sched& S, const Epi& E, const int tid) {
;     ...
;             PG8_LDA(At, 1, 1); PG8_STAGE(PG8_SB(1, 0), b3, voffB); PG8_STAGE(PG8_SB(1, 1), b3 + hstep, voffB); PG8_STAGE(PG8_SA(1, 0), a3, voffA);
;             PG8_WAIT_V(8); PG8_WAIT_L(0); PG8_BAR; PG8_MMA(1, 0, At, B0); PG8_MMA(1, 1, At, B1); PG8_BAR; PG8_SCHED;
;         }
	s_add_i32 s30, s67, s20
	v_lshl_add_u64 v[152:153], v[152:153], 0, s[74:75]
	s_mov_b32 m0, s30
	ds_read_b128 v[210:213], v143 offset:49152
	ds_read_b128 v[214:217], v143 offset:50176
	ds_read_b128 v[218:221], v143 offset:51200
	ds_read_b128 v[222:225], v143 offset:52224
	ds_read_b128 v[226:229], v143 offset:53248
	ds_read_b128 v[230:233], v143 offset:54272
	ds_read_b128 v[234:237], v143 offset:55296
	ds_read_b128 v[238:241], v143 offset:56320
	global_load_lds_dwordx4 v[152:153], off
	v_lshl_add_u64 v[152:153], v[198:199], 0, s[74:75]
	s_add_i32 m0, s30, 0x2000
	s_add_i32 s30, s68, s20
	global_load_lds_dwordx4 v[152:153], off
	v_lshl_add_u64 v[152:153], v[200:201], 0, s[74:75]
	s_mov_b32 m0, s30
	s_nop 0
	global_load_lds_dwordx4 v[152:153], off
	v_lshl_add_u64 v[152:153], v[242:243], 0, s[74:75]
	s_add_i32 m0, s30, 0x2000
	s_nop 0
	global_load_lds_dwordx4 v[152:153], off
	v_lshl_add_u64 v[152:153], v[244:245], 0, s[74:75]
	s_mov_b32 m0, s27
	s_nop 0
	global_load_lds_dwordx4 v[152:153], off
	v_lshl_add_u64 v[152:153], v[246:247], 0, s[74:75]
	s_mov_b32 m0, s34
	s_nop 0
	global_load_lds_dwordx4 v[152:153], off
	s_waitcnt vmcnt(8)
	s_waitcnt lgkmcnt(0)
	s_barrier
	s_setprio 1
	s_waitcnt lgkmcnt(0)
	v_mfma_f32_16x16x32_bf16 v[62:65], v[144:147], v[210:213], v[62:65]
	v_mfma_f32_16x16x32_bf16 v[54:57], v[144:147], v[218:221], v[54:57]
	v_mfma_f32_16x16x32_bf16 v[38:41], v[144:147], v[226:229], v[38:41]
	v_mfma_f32_16x16x32_bf16 v[22:25], v[144:147], v[234:237], v[22:25]
	v_mfma_f32_16x16x32_bf16 v[14:17], v[174:177], v[234:237], v[14:17]
	v_mfma_f32_16x16x32_bf16 v[30:33], v[174:177], v[226:229], v[30:33]
	v_mfma_f32_16x16x32_bf16 v[46:49], v[174:177], v[218:221], v[46:49]
	v_mfma_f32_16x16x32_bf16 v[58:61], v[174:177], v[210:213], v[58:61]
	v_mfma_f32_16x16x32_bf16 v[62:65], v[148:151], v[214:217], v[62:65]
	v_mfma_f32_16x16x32_bf16 v[54:57], v[148:151], v[222:225], v[54:57]
	v_mfma_f32_16x16x32_bf16 v[38:41], v[148:151], v[230:233], v[38:41]
	v_mfma_f32_16x16x32_bf16 v[22:25], v[148:151], v[238:241], v[22:25]
	v_mfma_f32_16x16x32_bf16 v[14:17], v[178:181], v[238:241], v[14:17]
	v_mfma_f32_16x16x32_bf16 v[30:33], v[178:181], v[230:233], v[30:33]
	v_mfma_f32_16x16x32_bf16 v[46:49], v[178:181], v[222:225], v[46:49]
	v_mfma_f32_16x16x32_bf16 v[58:61], v[178:181], v[214:217], v[58:61]
	s_setprio 0
	s_setprio 1
	v_mfma_f32_16x16x32_bf16 v[50:53], v[182:185], v[210:213], v[50:53]
	v_mfma_f32_16x16x32_bf16 v[34:37], v[182:185], v[218:221], v[34:37]
	v_mfma_f32_16x16x32_bf16 v[18:21], v[182:185], v[226:229], v[18:21]
	v_mfma_f32_16x16x32_bf16 v[6:9], v[182:185], v[234:237], v[6:9]
	v_mfma_f32_16x16x32_bf16 v[2:5], v[190:193], v[234:237], v[2:5]
	v_mfma_f32_16x16x32_bf16 v[10:13], v[190:193], v[226:229], v[10:13]
	v_mfma_f32_16x16x32_bf16 v[26:29], v[190:193], v[218:221], v[26:29]
	v_mfma_f32_16x16x32_bf16 v[42:45], v[190:193], v[210:213], v[42:45]
	v_mfma_f32_16x16x32_bf16 v[50:53], v[186:189], v[214:217], v[50:53]
	v_mfma_f32_16x16x32_bf16 v[34:37], v[186:189], v[222:225], v[34:37]
	v_mfma_f32_16x16x32_bf16 v[18:21], v[186:189], v[230:233], v[18:21]
	v_mfma_f32_16x16x32_bf16 v[6:9], v[186:189], v[238:241], v[6:9]
	v_mfma_f32_16x16x32_bf16 v[2:5], v[194:197], v[238:241], v[2:5]
	v_mfma_f32_16x16x32_bf16 v[10:13], v[194:197], v[230:233], v[10:13]
	v_mfma_f32_16x16x32_bf16 v[26:29], v[194:197], v[222:225], v[26:29]
	v_mfma_f32_16x16x32_bf16 v[42:45], v[194:197], v[214:217], v[42:45]
	s_setprio 0
	s_barrier
	s_add_u32 s42, s42, 0x100
	s_addc_u32 s43, s43, 0
	s_add_u32 s62, s62, 0x100
	s_addc_u32 s63, s63, 0
	s_cmp_ge_u32 s66, s35
	s_mov_b32 s31, s66
	s_cbranch_scc0 .LBB0_480
	s_and_b64 vcc, exec, s[58:59]
	s_cbranch_vccz .LBB0_483
	s_barrier
